# combine chain: in-place C-term prefetch issued right after the step barrier instead of before it
# speedup vs baseline: 1.0043x; 1.0028x over previous
.LBB0_500:
	s_min_u32 s2, s12, 0x76
	s_mulk_i32 s2, 0x6000
	s_lshl_b32 s10, s2, 2
	s_mov_b32 s11, s73
	s_waitcnt lgkmcnt(0)
	s_barrier
	global_load_dwordx4 v[58:61], v[244:245], off
	s_waitcnt vmcnt(16)
	ds_write_b128 v81, v[14:17]
	ds_write_b128 v81, v[10:13] offset:16
	v_lshl_add_u64 v[10:11], v[90:91], 0, s[10:11]
	s_mov_b64 s[16:17], 0xc0000
	v_lshl_add_u64 v[12:13], v[10:11], 0, s[16:17]
	v_add_co_u32_e32 v10, vcc, 0xc0000, v10
	v_lshl_add_u64 v[244:245], v[88:89], 0, s[72:73]
	s_nop 0
	v_addc_co_u32_e32 v11, vcc, 0, v11, vcc
	v_add_co_u32_e32 v244, vcc, 0xa8000, v244
	global_load_dwordx4 v[14:17], v[10:11], off
	s_nop 0
	global_load_dwordx4 v[10:13], v[12:13], off offset:16
	v_addc_co_u32_e32 v245, vcc, 0, v245, vcc
	s_and_b64 vcc, exec, s[6:7]
	v_add_u32_e32 v0, 0x8000, v179
	s_cbranch_vccnz .LBB0_502
	ds_read2st64_b32 v[200:201], v175 offset0:64 offset1:68
	ds_read2st64_b32 v[216:217], v176 offset0:144 offset1:145
	ds_read2st64_b32 v[202:203], v175 offset0:72 offset1:76
	ds_read2st64_b32 v[218:219], v176 offset0:146 offset1:147
	ds_read2st64_b32 v[204:205], v175 offset0:80 offset1:84
	ds_read2st64_b32 v[220:221], v176 offset0:148 offset1:149
	ds_read2st64_b32 v[206:207], v175 offset0:88 offset1:92
	ds_read2st64_b32 v[222:223], v176 offset0:150 offset1:151
	ds_read2st64_b32 v[208:209], v175 offset0:96 offset1:100
	ds_read2st64_b32 v[224:225], v176 offset0:152 offset1:153
	ds_read2st64_b32 v[210:211], v175 offset0:104 offset1:108
	ds_read2st64_b32 v[226:227], v176 offset0:154 offset1:155
	s_waitcnt vmcnt(16) lgkmcnt(10)
	v_mfma_f32_16x16x4_f32 v[66:69], v200, v216, v[66:69]
	v_mfma_f32_16x16x4_f32 v[94:97], v201, v217, 0
	ds_read2st64_b32 v[212:213], v175 offset0:112 offset1:116
	ds_read2st64_b32 v[228:229], v176 offset0:156 offset1:157
	s_waitcnt lgkmcnt(10)
	v_mfma_f32_16x16x4_f32 v[66:69], v202, v218, v[66:69]
	v_mfma_f32_16x16x4_f32 v[94:97], v203, v219, v[94:97]
	ds_read2st64_b32 v[214:215], v175 offset0:120 offset1:124
	ds_read2st64_b32 v[230:231], v176 offset0:158 offset1:159
	s_waitcnt lgkmcnt(10)
	v_mfma_f32_16x16x4_f32 v[66:69], v204, v220, v[66:69]
	v_mfma_f32_16x16x4_f32 v[94:97], v205, v221, v[94:97]
	s_waitcnt lgkmcnt(8)
	v_mfma_f32_16x16x4_f32 v[66:69], v206, v222, v[66:69]
	v_mfma_f32_16x16x4_f32 v[94:97], v207, v223, v[94:97]
	s_waitcnt lgkmcnt(6)
	v_mfma_f32_16x16x4_f32 v[66:69], v208, v224, v[66:69]
	v_mfma_f32_16x16x4_f32 v[94:97], v209, v225, v[94:97]
	s_waitcnt lgkmcnt(4)
	v_mfma_f32_16x16x4_f32 v[66:69], v210, v226, v[66:69]
	v_mfma_f32_16x16x4_f32 v[94:97], v211, v227, v[94:97]
	s_waitcnt lgkmcnt(2)
	v_mfma_f32_16x16x4_f32 v[66:69], v212, v228, v[66:69]
	v_mfma_f32_16x16x4_f32 v[94:97], v213, v229, v[94:97]
	s_waitcnt lgkmcnt(0)
	v_mfma_f32_16x16x4_f32 v[66:69], v214, v230, v[66:69]
	v_mfma_f32_16x16x4_f32 v[94:97], v215, v231, v[94:97]
	s_nop 9
	v_pk_add_f32 v[66:67], v[66:67], v[94:95]
	v_add_co_u32_e32 v94, vcc, 0x18000, v92
	v_pk_add_f32 v[68:69], v[68:69], v[96:97]
	s_nop 0
	v_addc_co_u32_e32 v95, vcc, 0, v93, vcc
	global_store_dwordx4 v[94:95], v[66:69], off
	ds_write2_b32 v0, v66, v67 offset1:16
	ds_write2_b32 v0, v68, v69 offset0:32 offset1:48
.LBB0_502:
	s_min_u32 s2, s12, 0x75
	s_mulk_i32 s2, 0x6000
	s_lshl_b32 s72, s2, 2
	s_waitcnt lgkmcnt(0)
	s_barrier
	global_load_dwordx4 v[66:69], v[244:245], off
	s_waitcnt vmcnt(17)
	ds_write_b128 v81, v[18:21] offset:16384
	s_waitcnt vmcnt(16)
	ds_write_b128 v81, v[22:25] offset:16400
	v_lshl_add_u64 v[18:19], v[90:91], 0, s[72:73]
	s_mov_b64 s[16:17], 0xd8000
	v_lshl_add_u64 v[22:23], v[18:19], 0, s[16:17]
	v_add_co_u32_e32 v18, vcc, 0xd8000, v18
	v_lshl_add_u64 v[244:245], v[88:89], 0, s[10:11]
	s_nop 0
	v_addc_co_u32_e32 v19, vcc, 0, v19, vcc
	v_add_co_u32_e32 v244, vcc, 0xc0000, v244
	global_load_dwordx4 v[18:21], v[18:19], off
	s_nop 0
	global_load_dwordx4 v[22:25], v[22:23], off offset:16
	v_addc_co_u32_e32 v245, vcc, 0, v245, vcc
	s_and_b64 vcc, exec, s[6:7]
	s_cbranch_vccnz .LBB0_504
	ds_read2st64_b32 v[200:201], v175 offset1:4
	ds_read2st64_b32 v[216:217], v176 offset0:128 offset1:129
	ds_read2st64_b32 v[202:203], v175 offset0:8 offset1:12
	ds_read2st64_b32 v[218:219], v176 offset0:130 offset1:131
	ds_read2st64_b32 v[204:205], v175 offset0:16 offset1:20
	ds_read2st64_b32 v[220:221], v176 offset0:132 offset1:133
	ds_read2st64_b32 v[206:207], v175 offset0:24 offset1:28
	ds_read2st64_b32 v[222:223], v176 offset0:134 offset1:135
	ds_read2st64_b32 v[208:209], v175 offset0:32 offset1:36
	ds_read2st64_b32 v[224:225], v176 offset0:136 offset1:137
	ds_read2st64_b32 v[210:211], v175 offset0:40 offset1:44
	ds_read2st64_b32 v[226:227], v176 offset0:138 offset1:139
	s_waitcnt vmcnt(16) lgkmcnt(10)
	v_mfma_f32_16x16x4_f32 v[74:77], v200, v216, v[74:77]
	v_mfma_f32_16x16x4_f32 v[94:97], v201, v217, 0
	ds_read2st64_b32 v[212:213], v175 offset0:48 offset1:52
	ds_read2st64_b32 v[228:229], v176 offset0:140 offset1:141
	s_waitcnt lgkmcnt(10)
	v_mfma_f32_16x16x4_f32 v[74:77], v202, v218, v[74:77]
	v_mfma_f32_16x16x4_f32 v[94:97], v203, v219, v[94:97]
	ds_read2st64_b32 v[214:215], v175 offset0:56 offset1:60
	ds_read2st64_b32 v[230:231], v176 offset0:142 offset1:143
	s_waitcnt lgkmcnt(10)
	v_mfma_f32_16x16x4_f32 v[74:77], v204, v220, v[74:77]
	v_mfma_f32_16x16x4_f32 v[94:97], v205, v221, v[94:97]
	s_waitcnt lgkmcnt(8)
	v_mfma_f32_16x16x4_f32 v[74:77], v206, v222, v[74:77]
	v_mfma_f32_16x16x4_f32 v[94:97], v207, v223, v[94:97]
	s_waitcnt lgkmcnt(6)
	v_mfma_f32_16x16x4_f32 v[74:77], v208, v224, v[74:77]
	v_mfma_f32_16x16x4_f32 v[94:97], v209, v225, v[94:97]
	s_waitcnt lgkmcnt(4)
	v_mfma_f32_16x16x4_f32 v[74:77], v210, v226, v[74:77]
	v_mfma_f32_16x16x4_f32 v[94:97], v211, v227, v[94:97]
	s_waitcnt lgkmcnt(2)
	v_mfma_f32_16x16x4_f32 v[74:77], v212, v228, v[74:77]
	v_mfma_f32_16x16x4_f32 v[94:97], v213, v229, v[94:97]
	s_waitcnt lgkmcnt(0)
	v_mfma_f32_16x16x4_f32 v[74:77], v214, v230, v[74:77]
	v_mfma_f32_16x16x4_f32 v[94:97], v215, v231, v[94:97]
	s_nop 9
	v_pk_add_f32 v[74:75], v[74:75], v[94:95]
	v_add_co_u32_e32 v94, vcc, 0x30000, v92
	v_pk_add_f32 v[76:77], v[76:77], v[96:97]
	s_nop 0
	v_addc_co_u32_e32 v95, vcc, 0, v93, vcc
	global_store_dwordx4 v[94:95], v[74:77], off
	v_add_u32_e32 v94, 0x9000, v179
	ds_write2_b32 v94, v74, v75 offset1:16
	ds_write2_b32 v94, v76, v77 offset0:32 offset1:48
.LBB0_504:
	s_min_u32 s2, s12, 0x74
	s_mulk_i32 s2, 0x6000
	s_lshl_b32 s10, s2, 2
	s_mov_b32 s11, s73
	s_waitcnt lgkmcnt(0)
	s_barrier
	global_load_dwordx4 v[74:77], v[244:245], off
	s_waitcnt vmcnt(16)
	ds_write_b128 v81, v[30:33]
	ds_write_b128 v81, v[26:29] offset:16
	v_lshl_add_u64 v[26:27], v[90:91], 0, s[10:11]
	s_mov_b64 s[16:17], 0xf0000
	v_lshl_add_u64 v[28:29], v[26:27], 0, s[16:17]
	v_add_co_u32_e32 v26, vcc, 0xf0000, v26
	v_lshl_add_u64 v[244:245], v[88:89], 0, s[72:73]
	s_nop 0
	v_addc_co_u32_e32 v27, vcc, 0, v27, vcc
	v_add_co_u32_e32 v244, vcc, 0xd8000, v244
	global_load_dwordx4 v[30:33], v[26:27], off
	s_nop 0
	global_load_dwordx4 v[26:29], v[28:29], off offset:16
	v_addc_co_u32_e32 v245, vcc, 0, v245, vcc
	s_and_b64 vcc, exec, s[6:7]
	s_cbranch_vccnz .LBB0_506
	ds_read2st64_b32 v[200:201], v175 offset0:64 offset1:68
	ds_read2st64_b32 v[216:217], v176 offset0:144 offset1:145
	ds_read2st64_b32 v[202:203], v175 offset0:72 offset1:76
	ds_read2st64_b32 v[218:219], v176 offset0:146 offset1:147
	ds_read2st64_b32 v[204:205], v175 offset0:80 offset1:84
	ds_read2st64_b32 v[220:221], v176 offset0:148 offset1:149
	ds_read2st64_b32 v[206:207], v175 offset0:88 offset1:92
	ds_read2st64_b32 v[222:223], v176 offset0:150 offset1:151
	ds_read2st64_b32 v[208:209], v175 offset0:96 offset1:100
	ds_read2st64_b32 v[224:225], v176 offset0:152 offset1:153
	ds_read2st64_b32 v[210:211], v175 offset0:104 offset1:108
	ds_read2st64_b32 v[226:227], v176 offset0:154 offset1:155
	s_waitcnt vmcnt(16) lgkmcnt(10)
	v_mfma_f32_16x16x4_f32 v[70:73], v200, v216, v[70:73]
	v_mfma_f32_16x16x4_f32 v[94:97], v201, v217, 0
	ds_read2st64_b32 v[212:213], v175 offset0:112 offset1:116
	ds_read2st64_b32 v[228:229], v176 offset0:156 offset1:157
	s_waitcnt lgkmcnt(10)
	v_mfma_f32_16x16x4_f32 v[70:73], v202, v218, v[70:73]
	v_mfma_f32_16x16x4_f32 v[94:97], v203, v219, v[94:97]
	ds_read2st64_b32 v[214:215], v175 offset0:120 offset1:124
	ds_read2st64_b32 v[230:231], v176 offset0:158 offset1:159
	s_waitcnt lgkmcnt(10)
	v_mfma_f32_16x16x4_f32 v[70:73], v204, v220, v[70:73]
	v_mfma_f32_16x16x4_f32 v[94:97], v205, v221, v[94:97]
	s_waitcnt lgkmcnt(8)
	v_mfma_f32_16x16x4_f32 v[70:73], v206, v222, v[70:73]
	v_mfma_f32_16x16x4_f32 v[94:97], v207, v223, v[94:97]
	s_waitcnt lgkmcnt(6)
	v_mfma_f32_16x16x4_f32 v[70:73], v208, v224, v[70:73]
	v_mfma_f32_16x16x4_f32 v[94:97], v209, v225, v[94:97]
	s_waitcnt lgkmcnt(4)
	v_mfma_f32_16x16x4_f32 v[70:73], v210, v226, v[70:73]
	v_mfma_f32_16x16x4_f32 v[94:97], v211, v227, v[94:97]
	s_waitcnt lgkmcnt(2)
	v_mfma_f32_16x16x4_f32 v[70:73], v212, v228, v[70:73]
	v_mfma_f32_16x16x4_f32 v[94:97], v213, v229, v[94:97]
	s_waitcnt lgkmcnt(0)
	v_mfma_f32_16x16x4_f32 v[70:73], v214, v230, v[70:73]
	v_mfma_f32_16x16x4_f32 v[94:97], v215, v231, v[94:97]
	s_nop 9
	v_pk_add_f32 v[70:71], v[70:71], v[94:95]
	v_add_co_u32_e32 v94, vcc, 0x48000, v92
	v_pk_add_f32 v[72:73], v[72:73], v[96:97]
	s_nop 0
	v_addc_co_u32_e32 v95, vcc, 0, v93, vcc
	global_store_dwordx4 v[94:95], v[70:73], off
	ds_write2_b32 v0, v70, v71 offset1:16
	ds_write2_b32 v0, v72, v73 offset0:32 offset1:48
.LBB0_506:
	s_min_u32 s2, s12, 0x73
	s_mulk_i32 s2, 0x6000
	s_lshl_b32 s72, s2, 2
	s_waitcnt lgkmcnt(0)
	s_barrier
	global_load_dwordx4 v[70:73], v[244:245], off
	s_waitcnt vmcnt(17)
	ds_write_b128 v81, v[34:37] offset:16384
	s_waitcnt vmcnt(16)
	ds_write_b128 v81, v[38:41] offset:16400
	v_lshl_add_u64 v[34:35], v[90:91], 0, s[72:73]
	s_mov_b64 s[16:17], 0x108000
	v_lshl_add_u64 v[38:39], v[34:35], 0, s[16:17]
	v_add_co_u32_e32 v34, vcc, 0x108000, v34
	v_lshl_add_u64 v[244:245], v[88:89], 0, s[10:11]
	s_nop 0
	v_addc_co_u32_e32 v35, vcc, 0, v35, vcc
	v_add_co_u32_e32 v244, vcc, 0xf0000, v244
	global_load_dwordx4 v[34:37], v[34:35], off
	s_nop 0
	global_load_dwordx4 v[38:41], v[38:39], off offset:16
	v_addc_co_u32_e32 v245, vcc, 0, v245, vcc
	s_and_b64 vcc, exec, s[6:7]
	s_cbranch_vccnz .LBB0_508
	ds_read2st64_b32 v[200:201], v175 offset1:4
	ds_read2st64_b32 v[216:217], v176 offset0:128 offset1:129
	ds_read2st64_b32 v[202:203], v175 offset0:8 offset1:12
	ds_read2st64_b32 v[218:219], v176 offset0:130 offset1:131
	ds_read2st64_b32 v[204:205], v175 offset0:16 offset1:20
	ds_read2st64_b32 v[220:221], v176 offset0:132 offset1:133
	ds_read2st64_b32 v[206:207], v175 offset0:24 offset1:28
	ds_read2st64_b32 v[222:223], v176 offset0:134 offset1:135
	ds_read2st64_b32 v[208:209], v175 offset0:32 offset1:36
	ds_read2st64_b32 v[224:225], v176 offset0:136 offset1:137
	ds_read2st64_b32 v[210:211], v175 offset0:40 offset1:44
	ds_read2st64_b32 v[226:227], v176 offset0:138 offset1:139
	s_waitcnt vmcnt(16) lgkmcnt(10)
	v_mfma_f32_16x16x4_f32 v[62:65], v200, v216, v[62:65]
	v_mfma_f32_16x16x4_f32 v[94:97], v201, v217, 0
	ds_read2st64_b32 v[212:213], v175 offset0:48 offset1:52
	ds_read2st64_b32 v[228:229], v176 offset0:140 offset1:141
	s_waitcnt lgkmcnt(10)
	v_mfma_f32_16x16x4_f32 v[62:65], v202, v218, v[62:65]
	v_mfma_f32_16x16x4_f32 v[94:97], v203, v219, v[94:97]
	ds_read2st64_b32 v[214:215], v175 offset0:56 offset1:60
	ds_read2st64_b32 v[230:231], v176 offset0:142 offset1:143
	s_waitcnt lgkmcnt(10)
	v_mfma_f32_16x16x4_f32 v[62:65], v204, v220, v[62:65]
	v_mfma_f32_16x16x4_f32 v[94:97], v205, v221, v[94:97]
	s_waitcnt lgkmcnt(8)
	v_mfma_f32_16x16x4_f32 v[62:65], v206, v222, v[62:65]
	v_mfma_f32_16x16x4_f32 v[94:97], v207, v223, v[94:97]
	s_waitcnt lgkmcnt(6)
	v_mfma_f32_16x16x4_f32 v[62:65], v208, v224, v[62:65]
	v_mfma_f32_16x16x4_f32 v[94:97], v209, v225, v[94:97]
	s_waitcnt lgkmcnt(4)
	v_mfma_f32_16x16x4_f32 v[62:65], v210, v226, v[62:65]
	v_mfma_f32_16x16x4_f32 v[94:97], v211, v227, v[94:97]
	s_waitcnt lgkmcnt(2)
	v_mfma_f32_16x16x4_f32 v[62:65], v212, v228, v[62:65]
	v_mfma_f32_16x16x4_f32 v[94:97], v213, v229, v[94:97]
	s_waitcnt lgkmcnt(0)
	v_mfma_f32_16x16x4_f32 v[62:65], v214, v230, v[62:65]
	v_mfma_f32_16x16x4_f32 v[94:97], v215, v231, v[94:97]
	s_nop 9
	v_pk_add_f32 v[62:63], v[62:63], v[94:95]
	v_add_co_u32_e32 v94, vcc, 0x60000, v92
	v_pk_add_f32 v[64:65], v[64:65], v[96:97]
	s_nop 0
	v_addc_co_u32_e32 v95, vcc, 0, v93, vcc
	global_store_dwordx4 v[94:95], v[62:65], off
	v_add_u32_e32 v94, 0x9000, v179
	ds_write2_b32 v94, v62, v63 offset1:16
	ds_write2_b32 v94, v64, v65 offset0:32 offset1:48
.LBB0_508:
	s_min_u32 s2, s12, 0x72
	s_mul_i32 s10, s2, 0x18000
	s_mov_b32 s11, s73
	s_waitcnt lgkmcnt(0)
	s_barrier
	global_load_dwordx4 v[62:65], v[244:245], off
	s_waitcnt vmcnt(16)
	ds_write_b128 v81, v[46:49]
	ds_write_b128 v81, v[42:45] offset:16
	v_lshl_add_u64 v[42:43], v[90:91], 0, s[10:11]
	s_mov_b64 s[10:11], 0x120000
	v_lshl_add_u64 v[44:45], v[42:43], 0, s[10:11]
	v_add_co_u32_e32 v42, vcc, 0x120000, v42
	v_lshl_add_u64 v[244:245], v[88:89], 0, s[72:73]
	s_nop 0
	v_addc_co_u32_e32 v43, vcc, 0, v43, vcc
	v_add_co_u32_e32 v244, vcc, 0x108000, v244
	global_load_dwordx4 v[46:49], v[42:43], off
	s_nop 0
	global_load_dwordx4 v[42:45], v[44:45], off offset:16
	v_addc_co_u32_e32 v245, vcc, 0, v245, vcc
	s_and_b64 vcc, exec, s[6:7]
	s_cbranch_vccnz .LBB0_510
	ds_read2st64_b32 v[200:201], v175 offset0:64 offset1:68
	ds_read2st64_b32 v[216:217], v176 offset0:144 offset1:145
	ds_read2st64_b32 v[202:203], v175 offset0:72 offset1:76
	ds_read2st64_b32 v[218:219], v176 offset0:146 offset1:147
	ds_read2st64_b32 v[204:205], v175 offset0:80 offset1:84
	ds_read2st64_b32 v[220:221], v176 offset0:148 offset1:149
	ds_read2st64_b32 v[206:207], v175 offset0:88 offset1:92
	ds_read2st64_b32 v[222:223], v176 offset0:150 offset1:151
	ds_read2st64_b32 v[208:209], v175 offset0:96 offset1:100
	ds_read2st64_b32 v[224:225], v176 offset0:152 offset1:153
	ds_read2st64_b32 v[210:211], v175 offset0:104 offset1:108
	ds_read2st64_b32 v[226:227], v176 offset0:154 offset1:155
	s_waitcnt vmcnt(16) lgkmcnt(10)
	v_mfma_f32_16x16x4_f32 v[54:57], v200, v216, v[54:57]
	v_mfma_f32_16x16x4_f32 v[94:97], v201, v217, 0
	ds_read2st64_b32 v[212:213], v175 offset0:112 offset1:116
	ds_read2st64_b32 v[228:229], v176 offset0:156 offset1:157
	s_waitcnt lgkmcnt(10)
	v_mfma_f32_16x16x4_f32 v[54:57], v202, v218, v[54:57]
	v_mfma_f32_16x16x4_f32 v[94:97], v203, v219, v[94:97]
	ds_read2st64_b32 v[214:215], v175 offset0:120 offset1:124
	ds_read2st64_b32 v[230:231], v176 offset0:158 offset1:159
	s_waitcnt lgkmcnt(10)
	v_mfma_f32_16x16x4_f32 v[54:57], v204, v220, v[54:57]
	v_mfma_f32_16x16x4_f32 v[94:97], v205, v221, v[94:97]
	s_waitcnt lgkmcnt(8)
	v_mfma_f32_16x16x4_f32 v[54:57], v206, v222, v[54:57]
	v_mfma_f32_16x16x4_f32 v[94:97], v207, v223, v[94:97]
	s_waitcnt lgkmcnt(6)
	v_mfma_f32_16x16x4_f32 v[54:57], v208, v224, v[54:57]
	v_mfma_f32_16x16x4_f32 v[94:97], v209, v225, v[94:97]
	s_waitcnt lgkmcnt(4)
	v_mfma_f32_16x16x4_f32 v[54:57], v210, v226, v[54:57]
	v_mfma_f32_16x16x4_f32 v[94:97], v211, v227, v[94:97]
	s_waitcnt lgkmcnt(2)
	v_mfma_f32_16x16x4_f32 v[54:57], v212, v228, v[54:57]
	v_mfma_f32_16x16x4_f32 v[94:97], v213, v229, v[94:97]
	s_waitcnt lgkmcnt(0)
	v_mfma_f32_16x16x4_f32 v[54:57], v214, v230, v[54:57]
	v_mfma_f32_16x16x4_f32 v[94:97], v215, v231, v[94:97]
	s_nop 9
	v_pk_add_f32 v[54:55], v[54:55], v[94:95]
	v_add_co_u32_e32 v94, vcc, 0x78000, v92
	v_pk_add_f32 v[56:57], v[56:57], v[96:97]
	s_nop 0
	v_addc_co_u32_e32 v95, vcc, 0, v93, vcc
	global_store_dwordx4 v[94:95], v[54:57], off
	ds_write2_b32 v0, v54, v55 offset1:16
	ds_write2_b32 v0, v56, v57 offset0:32 offset1:48
.LBB0_510:
	s_waitcnt lgkmcnt(0)
	s_barrier
	global_load_dwordx4 v[54:57], v[244:245], off
	v_lshl_add_u64 v[92:93], v[92:93], 0, s[88:89]
	s_cmpk_gt_u32 s12, 0x77
	s_cbranch_scc1 .LBB0_512
	s_branch .LBB0_498
